# non-leader workgroups poll the chip-wide generation word (TOPGEN) instead of their XCD's: one notification hop less (on top of early acquire invalidate)
# baseline (speedup 1.0000x reference)
; __device__ __forceinline__ unsigned xb_ld(unsigned* p)              { return __hip_atomic_load(p, __ATOMIC_RELAXED, __HIP_MEMORY_SCOPE_AGENT); }
; __device__ __forceinline__ unsigned xb_add(unsigned* p, unsigned v) { return __hip_atomic_fetch_add(p, v, __ATOMIC_RELAXED, __HIP_MEMORY_SCOPE_AGENT); }
; #define XB_SPIN(cond, bar) do { unsigned _sp = 0; while (cond) { __builtin_amdgcn_s_sleep(1); \
;     if ((++_sp & 255u) == 0u) { if (xb_ld(&(bar)[XB_TMO])) break; if (_sp > XB_SPIN_CAP) { atomicAdd(&(bar)[XB_TMO], 1u); break; } } } } while (0)
; __device__ __forceinline__ void xcd_barrier(const XcdBarrier& b) {
;     ...
;         const unsigned gen = old / nloc;
;         if (old + 1u == (gen + 1u) * nloc) {
;             __builtin_amdgcn_fence(__ATOMIC_RELEASE, "agent");
;             asm volatile("s_waitcnt vmcnt(0)" ::: "memory");
;             const unsigned og = xb_add(&bar[XB_TOP], 1u);
;             const unsigned tg = og / nx;
;             if (og + 1u == (tg + 1u) * nx) xb_add(&bar[XB_TOPGEN], 1u);
;             else XB_SPIN(xb_ld(&bar[XB_TOPGEN]) == tg, bar);
;             __builtin_amdgcn_fence(__ATOMIC_ACQUIRE, "agent");
;             xb_add(&bar[XB_XGEN(b.x)], 1u);
;             asm volatile("s_waitcnt vmcnt(0)" ::: "memory");
;         } else {
;             XB_SPIN(xb_ld(&bar[XB_XGEN(b.x)]) == gen, bar);
.LBB0_113:
	s_or_b64 exec, exec, s[8:9]
	v_cvt_f32_u32_e32 v5, v3
	s_waitcnt vmcnt(0)
	v_readfirstlane_b32 s6, v4
	v_sub_u32_e32 v4, 0, v3
	v_rcp_iflag_f32_e32 v5, v5
	v_add_u32_e32 v6, s6, v2
	v_mul_f32_e32 v5, 0x4f7ffffe, v5
	v_cvt_u32_f32_e32 v5, v5
	v_mul_lo_u32 v2, v4, v5
	v_mul_hi_u32 v2, v5, v2
	v_add_u32_e32 v2, v5, v2
	v_mul_hi_u32 v2, v6, v2
	v_mul_lo_u32 v4, v2, v3
	v_sub_u32_e32 v4, v6, v4
	v_add_u32_e32 v5, 1, v2
	v_cmp_ge_u32_e32 vcc, v4, v3
	s_nop 1
	v_cndmask_b32_e32 v2, v2, v5, vcc
	v_sub_u32_e32 v5, v4, v3
	v_cndmask_b32_e32 v4, v4, v5, vcc
	v_add_u32_e32 v5, 1, v2
	v_cmp_ge_u32_e32 vcc, v4, v3
	v_add_u32_e32 v4, 1, v6
	s_nop 0
	v_cndmask_b32_e32 v2, v2, v5, vcc
	v_mul_lo_u32 v5, v3, v2
	v_add_u32_e32 v3, v5, v3
	v_cmp_ne_u32_e32 vcc, v4, v3
	s_and_saveexec_b64 s[6:7], vcc
	s_xor_b64 s[6:7], exec, s[6:7]
	s_cbranch_execz .LBB0_127
	s_waitcnt lgkmcnt(0)
	v_readlane_b32 s10, v254, 34
	v_readlane_b32 s11, v254, 35
	v_mov_b32_e32 v1, 0
	s_add_u32 s10, s10, 0x3500
	s_addc_u32 s11, s11, 0
	s_nop 4
	global_load_dword v1, v1, s[10:11] sc1
	s_waitcnt vmcnt(0)
	v_cmp_eq_u32_e32 vcc, v1, v2
	s_and_saveexec_b64 s[8:9], vcc
	s_cbranch_execz .LBB0_126
	s_mov_b32 s22, 1
	s_mov_b64 s[12:13], 0
	v_mov_b32_e32 v1, 0
	s_branch .LBB0_117

; __device__ __forceinline__ unsigned xb_ld(unsigned* p)              { return __hip_atomic_load(p, __ATOMIC_RELAXED, __HIP_MEMORY_SCOPE_AGENT); }
; __device__ __forceinline__ unsigned xb_add(unsigned* p, unsigned v) { return __hip_atomic_fetch_add(p, v, __ATOMIC_RELAXED, __HIP_MEMORY_SCOPE_AGENT); }
; #define XB_SPIN(cond, bar) do { unsigned _sp = 0; while (cond) { __builtin_amdgcn_s_sleep(1); \
;     if ((++_sp & 255u) == 0u) { if (xb_ld(&(bar)[XB_TMO])) break; if (_sp > XB_SPIN_CAP) { atomicAdd(&(bar)[XB_TMO], 1u); break; } } } } while (0)
; __device__ __forceinline__ void xcd_barrier(const XcdBarrier& b) {
;     ...
;         const unsigned gen = old / nloc;
;         if (old + 1u == (gen + 1u) * nloc) {
;             __builtin_amdgcn_fence(__ATOMIC_RELEASE, "agent");
;             asm volatile("s_waitcnt vmcnt(0)" ::: "memory");
;             const unsigned og = xb_add(&bar[XB_TOP], 1u);
;             const unsigned tg = og / nx;
;             if (og + 1u == (tg + 1u) * nx) xb_add(&bar[XB_TOPGEN], 1u);
;             else XB_SPIN(xb_ld(&bar[XB_TOPGEN]) == tg, bar);
;             __builtin_amdgcn_fence(__ATOMIC_ACQUIRE, "agent");
;             xb_add(&bar[XB_XGEN(b.x)], 1u);
;             asm volatile("s_waitcnt vmcnt(0)" ::: "memory");
;         } else {
;             XB_SPIN(xb_ld(&bar[XB_XGEN(b.x)]) == gen, bar);
.LBB0_1815:
	s_or_b64 exec, exec, s[6:7]
	v_cvt_f32_u32_e32 v5, v3
	s_waitcnt vmcnt(0)
	v_readfirstlane_b32 s4, v4
	v_sub_u32_e32 v4, 0, v3
	v_rcp_iflag_f32_e32 v5, v5
	v_add_u32_e32 v6, s4, v2
	v_mul_f32_e32 v5, 0x4f7ffffe, v5
	v_cvt_u32_f32_e32 v5, v5
	v_mul_lo_u32 v2, v4, v5
	v_mul_hi_u32 v2, v5, v2
	v_add_u32_e32 v2, v5, v2
	v_mul_hi_u32 v2, v6, v2
	v_mul_lo_u32 v4, v2, v3
	v_sub_u32_e32 v4, v6, v4
	v_add_u32_e32 v5, 1, v2
	v_cmp_ge_u32_e32 vcc, v4, v3
	s_nop 1
	v_cndmask_b32_e32 v2, v2, v5, vcc
	v_sub_u32_e32 v5, v4, v3
	v_cndmask_b32_e32 v4, v4, v5, vcc
	v_add_u32_e32 v5, 1, v2
	v_cmp_ge_u32_e32 vcc, v4, v3
	v_add_u32_e32 v4, 1, v6
	s_nop 0
	v_cndmask_b32_e32 v2, v2, v5, vcc
	v_mul_lo_u32 v5, v3, v2
	v_add_u32_e32 v3, v5, v3
	v_cmp_ne_u32_e32 vcc, v4, v3
	s_and_saveexec_b64 s[4:5], vcc
	s_xor_b64 s[4:5], exec, s[4:5]
	s_cbranch_execz .LBB0_1829
	s_waitcnt lgkmcnt(0)
	v_readlane_b32 s8, v254, 34
	v_readlane_b32 s9, v254, 35
	v_mov_b32_e32 v1, 0
	s_add_u32 s8, s8, 0x3500
	s_addc_u32 s9, s9, 0
	s_nop 4
	global_load_dword v1, v1, s[8:9] sc1
	s_waitcnt vmcnt(0)
	v_cmp_eq_u32_e32 vcc, v1, v2
	s_and_saveexec_b64 s[6:7], vcc
	s_cbranch_execz .LBB0_1828
	s_mov_b32 s20, 1
	s_mov_b64 s[10:11], 0
	v_mov_b32_e32 v1, 0
	s_branch .LBB0_1819

; __device__ __forceinline__ unsigned xb_ld(unsigned* p)              { return __hip_atomic_load(p, __ATOMIC_RELAXED, __HIP_MEMORY_SCOPE_AGENT); }
; __device__ __forceinline__ unsigned xb_add(unsigned* p, unsigned v) { return __hip_atomic_fetch_add(p, v, __ATOMIC_RELAXED, __HIP_MEMORY_SCOPE_AGENT); }
; #define XB_SPIN(cond, bar) do { unsigned _sp = 0; while (cond) { __builtin_amdgcn_s_sleep(1); \
;     if ((++_sp & 255u) == 0u) { if (xb_ld(&(bar)[XB_TMO])) break; if (_sp > XB_SPIN_CAP) { atomicAdd(&(bar)[XB_TMO], 1u); break; } } } } while (0)
; __device__ __forceinline__ void xcd_barrier(const XcdBarrier& b) {
;     ...
;         const unsigned gen = old / nloc;
;         if (old + 1u == (gen + 1u) * nloc) {
;             __builtin_amdgcn_fence(__ATOMIC_RELEASE, "agent");
;             asm volatile("s_waitcnt vmcnt(0)" ::: "memory");
;             const unsigned og = xb_add(&bar[XB_TOP], 1u);
;             const unsigned tg = og / nx;
;             if (og + 1u == (tg + 1u) * nx) xb_add(&bar[XB_TOPGEN], 1u);
;             else XB_SPIN(xb_ld(&bar[XB_TOPGEN]) == tg, bar);
;             __builtin_amdgcn_fence(__ATOMIC_ACQUIRE, "agent");
;             xb_add(&bar[XB_XGEN(b.x)], 1u);
;             asm volatile("s_waitcnt vmcnt(0)" ::: "memory");
;         } else {
;             XB_SPIN(xb_ld(&bar[XB_XGEN(b.x)]) == gen, bar);
.LBB0_2128:
	s_or_b64 exec, exec, s[12:13]
	v_cvt_f32_u32_e32 v5, v3
	s_waitcnt vmcnt(0)
	v_readfirstlane_b32 s7, v4
	v_sub_u32_e32 v4, 0, v3
	v_rcp_iflag_f32_e32 v5, v5
	v_add_u32_e32 v6, s7, v2
	v_mul_f32_e32 v5, 0x4f7ffffe, v5
	v_cvt_u32_f32_e32 v5, v5
	v_mul_lo_u32 v2, v4, v5
	v_mul_hi_u32 v2, v5, v2
	v_add_u32_e32 v2, v5, v2
	v_mul_hi_u32 v2, v6, v2
	v_mul_lo_u32 v4, v2, v3
	v_sub_u32_e32 v4, v6, v4
	v_add_u32_e32 v5, 1, v2
	v_cmp_ge_u32_e32 vcc, v4, v3
	s_nop 1
	v_cndmask_b32_e32 v2, v2, v5, vcc
	v_sub_u32_e32 v5, v4, v3
	v_cndmask_b32_e32 v4, v4, v5, vcc
	v_add_u32_e32 v5, 1, v2
	v_cmp_ge_u32_e32 vcc, v4, v3
	v_add_u32_e32 v4, 1, v6
	s_nop 0
	v_cndmask_b32_e32 v2, v2, v5, vcc
	v_mul_lo_u32 v5, v3, v2
	v_add_u32_e32 v3, v5, v3
	v_cmp_ne_u32_e32 vcc, v4, v3
	s_and_saveexec_b64 s[10:11], vcc
	s_xor_b64 s[10:11], exec, s[10:11]
	s_cbranch_execz .LBB0_2142
	s_waitcnt lgkmcnt(0)
	v_readlane_b32 s14, v254, 34
	v_readlane_b32 s15, v254, 35
	v_mov_b32_e32 v1, 0
	s_add_u32 s14, s14, 0x3500
	s_addc_u32 s15, s15, 0
	s_nop 4
	global_load_dword v1, v1, s[14:15] sc1
	s_waitcnt vmcnt(0)
	v_cmp_eq_u32_e32 vcc, v1, v2
	s_and_saveexec_b64 s[12:13], vcc
	s_cbranch_execz .LBB0_2141
	s_mov_b32 s7, 1
	s_mov_b64 s[16:17], 0
	v_mov_b32_e32 v1, 0
	s_branch .LBB0_2132
